# gmlp pre-phases: half the blocks run rownorm before the weight transposes, half after (overlap HBM-bound and latency-bound work)
# baseline (speedup 1.0000x reference)
.LBB0_17:
	s_cmp_lt_i32 s84, 1
	v_writelane_b32 v252, s0, 2
	s_load_dwordx16 s[60:75], s[0:1], 0x40
	s_cselect_b64 s[12:13], -1, 0
	s_cmp_gt_i32 s84, 0
	s_cselect_b64 s[4:5], -1, 0
	s_cmp_lt_i32 s85, 1
	s_cselect_b64 s[6:7], -1, 0
	s_or_b64 s[4:5], s[4:5], s[6:7]
	s_and_b64 vcc, exec, s[4:5]
	v_writelane_b32 v252, s1, 3
	s_cbranch_vccnz .LBB0_56
	s_bitcmp1_b32 s2, 3
	s_cbranch_scc1 .Lp0_rn
.Lp0_conv:
	s_cmpk_gt_i32 s2, 0x2ff
	s_cbranch_scc1 .LBB0_39
	v_and_b32_e32 v0, 15, v181
	v_lshrrev_b32_e32 v8, 4, v181
	v_lshlrev_b32_e32 v14, 2, v0
	v_lshlrev_b32_e32 v1, 9, v181
	s_movk_i32 s3, 0x101c
	v_lshrrev_b32_e32 v2, 5, v181
	v_bitop3_b32 v15, v14, s3, v1 bitop3:0xc8
	v_lshl_add_u32 v1, v0, 11, 0
	v_lshlrev_b32_e32 v10, 4, v0
	v_xor_b32_e32 v0, v14, v8
	v_bitop3_b32 v2, v2, v14, 28 bitop3:0x6c
	v_lshl_add_u32 v16, v0, 2, v1
	v_lshlrev_b32_e32 v0, 8, v8
	v_lshlrev_b32_e32 v2, 2, v2
	v_add_u32_e32 v18, 32, v8
	v_add3_u32 v17, 0, v0, v2
	v_lshrrev_b32_e32 v2, 1, v18
	v_bitop3_b32 v2, v2, v14, 60 bitop3:0x6c
	v_lshlrev_b32_e32 v0, 8, v18
	v_lshlrev_b32_e32 v2, 2, v2
	v_add3_u32 v19, 0, v0, v2
	v_or_b32_e32 v0, 64, v8
	v_lshlrev_b32_e32 v2, 8, v0
	v_lshrrev_b32_e32 v0, 1, v0
	v_bitop3_b32 v0, v0, v14, 60 bitop3:0x6c
	v_lshlrev_b32_e32 v0, 2, v0
	v_add3_u32 v20, 0, v2, v0
	v_add_u32_e32 v0, 0x60, v8
	v_lshlrev_b32_e32 v2, 8, v0
	v_lshrrev_b32_e32 v0, 1, v0
	s_movk_i32 s3, 0x7c
	v_bitop3_b32 v0, v0, v14, s3 bitop3:0x6c
	v_lshlrev_b32_e32 v0, 2, v0
	s_cmp_lg_u64 s[40:41], 0
	v_add3_u32 v21, 0, v2, v0
	v_xor_b32_e32 v0, v18, v14
	s_mul_i32 s4, s2, 0xc0000
	s_cselect_b64 s[8:9], -1, 0
	v_lshl_add_u32 v22, v0, 2, v1
	s_movk_i32 s5, 0x1800
	v_mov_b32_e32 v0, s4
	v_mov_b32_e32 v11, 0
	v_mad_u32_u24 v23, v8, s5, v0
	v_cndmask_b32_e64 v0, 0, 1, s[8:9]
	v_lshl_add_u64 v[12:13], s[34:35], 0, v[10:11]
	v_mov_b32_e32 v9, v11
	s_lshl_b32 s3, s2, 7
	s_lshl_b32 s16, s82, 7
	s_mul_i32 s17, s82, 0xc0000
	s_movk_i32 s18, 0x1000
	v_cmp_ne_u32_e64 s[4:5], 1, v0
	s_mov_b32 s19, s2
	s_branch .LBB0_21

.LBB0_46:
	s_bitcmp1_b32 s2, 3
	s_cbranch_scc1 .Lp0_end

.LBB0_55:
	s_or_b64 exec, exec, s[14:15]
	s_bitcmp1_b32 s2, 3
	s_cbranch_scc1 .Lp0_conv
.Lp0_end:
.LBB0_56:
	s_cmp_gt_i32 s85, 1
	s_cselect_b64 s[4:5], -1, 0
	s_and_b64 s[6:7], s[12:13], s[4:5]
	s_andn2_b64 vcc, exec, s[6:7]
	s_cbranch_vccnz .LBB0_110
	s_waitcnt vmcnt(0)
	s_waitcnt lgkmcnt(0)
	s_barrier
	s_and_saveexec_b64 s[6:7], s[94:95]
	s_cbranch_execz .LBB0_109
	s_add_i32 s3, 0, 0x24800
	v_mov_b32_e32 v0, s3
	s_waitcnt vmcnt(0) expcnt(0) lgkmcnt(0)
	ds_read_b32 v2, v0
	s_add_i32 s3, 0, 0x24804
	v_mov_b32_e32 v0, s3
	ds_read_b32 v0, v0
	s_waitcnt lgkmcnt(1)
	v_cmp_ne_u32_e32 vcc, 0, v2
	s_cbranch_vccnz .LBB0_73
	s_add_u32 s8, s34, 0x3e00200
	s_addc_u32 s9, s35, 0
	s_add_u32 s10, s34, 0x3e00400
	s_addc_u32 s11, s35, 0
	s_add_u32 s12, s34, 0x3e00500
	s_addc_u32 s13, s35, 0
	s_add_u32 s14, s34, 0x3e00600
	s_addc_u32 s15, s35, 0
	s_add_u32 s16, s34, 0x3e00700
	s_addc_u32 s17, s35, 0
	s_add_u32 s18, s34, 0x3e00800
	s_addc_u32 s19, s35, 0
	s_add_u32 s22, s34, 0x3e00900
	s_addc_u32 s23, s35, 0
	s_add_u32 s40, s34, 0x3e00a00
	s_addc_u32 s41, s35, 0
	s_add_u32 s42, s34, 0x3e00b00
	s_addc_u32 s43, s35, 0
	s_add_u32 s52, s34, 0x3e00c00
	s_addc_u32 s53, s35, 0
	s_add_u32 s54, s34, 0x3e00d00
	s_addc_u32 s55, s35, 0
	s_add_u32 s56, s34, 0x3e00e00
	s_addc_u32 s57, s35, 0
	s_add_u32 s58, s34, 0x3e00f00
	s_addc_u32 s59, s35, 0
	s_add_u32 s60, s34, 0x3e01000
	s_addc_u32 s61, s35, 0
	s_add_u32 s88, s34, 0x3e01100
	s_addc_u32 s89, s35, 0
	s_add_u32 s90, s34, 0x3e01200
	s_addc_u32 s91, s35, 0
	s_mov_b32 s21, s92
	s_mul_i32 s3, s83, s92
	s_add_u32 s92, s34, 0x3e01300
	s_mov_b64 s[0:1], s[84:85]
	s_mov_b64 s[84:85], s[80:81]
	s_mov_b64 s[80:81], s[94:95]
	s_mul_i32 s3, s3, s82
	s_addc_u32 s93, s35, 0
	s_mov_b32 s86, 1
	v_mov_b32_e32 v16, 0
	s_branch .LBB0_61

.LBB0_1391:
	s_cmp_lt_i32 s84, 19
	s_cselect_b64 s[10:11], -1, 0
	s_and_b64 s[0:1], s[10:11], s[4:5]
	s_andn2_b64 vcc, exec, s[0:1]
	s_cbranch_vccnz .LBB0_1430
	s_bitcmp1_b32 s2, 3
	s_cbranch_scc1 .Lp18_rn
.Lp18_conv:
	s_cmpk_gt_i32 s2, 0x2ff
	v_and_b32_e32 v15, 15, v181
	v_lshrrev_b32_e32 v8, 4, v181
	v_lshrrev_b32_e32 v14, 5, v181
	s_cbranch_scc1 .LBB0_1413
	v_lshlrev_b32_e32 v16, 2, v15
	v_lshlrev_b32_e32 v0, 9, v181
	s_movk_i32 s0, 0x101c
	v_bitop3_b32 v17, v16, s0, v0 bitop3:0xc8
	v_lshl_add_u32 v0, v15, 11, 0
	v_xor_b32_e32 v1, v16, v8
	v_bitop3_b32 v2, v14, v16, 28 bitop3:0x6c
	v_lshl_add_u32 v18, v1, 2, v0
	v_lshlrev_b32_e32 v1, 8, v8
	v_lshlrev_b32_e32 v2, 2, v2
	v_add_u32_e32 v20, 32, v8
	v_add3_u32 v19, 0, v1, v2
	v_lshrrev_b32_e32 v2, 1, v20
	v_bitop3_b32 v2, v2, v16, 60 bitop3:0x6c
	v_lshlrev_b32_e32 v1, 8, v20
	v_lshlrev_b32_e32 v2, 2, v2
	v_add3_u32 v21, 0, v1, v2
	v_or_b32_e32 v1, 64, v8
	v_lshlrev_b32_e32 v2, 8, v1
	v_lshrrev_b32_e32 v1, 1, v1
	v_bitop3_b32 v1, v1, v16, 60 bitop3:0x6c
	v_lshlrev_b32_e32 v1, 2, v1
	v_add3_u32 v22, 0, v2, v1
	v_add_u32_e32 v1, 0x60, v8
	v_lshlrev_b32_e32 v2, 8, v1
	v_lshrrev_b32_e32 v1, 1, v1
	s_movk_i32 s0, 0x7c
	v_bitop3_b32 v1, v1, v16, s0 bitop3:0x6c
	v_lshlrev_b32_e32 v1, 2, v1
	s_waitcnt lgkmcnt(0)
	s_cmp_lg_u64 s[50:51], 0
	v_add3_u32 v23, 0, v2, v1
	v_xor_b32_e32 v1, v20, v16
	s_mul_i32 s0, s2, 0xc0000
	s_cselect_b64 s[6:7], -1, 0
	v_lshl_add_u32 v24, v1, 2, v0
	s_movk_i32 s1, 0x1800
	v_mov_b32_e32 v0, s0
	v_mov_b32_e32 v11, 0
	v_lshlrev_b32_e32 v10, 4, v15
	v_mad_u32_u24 v25, v8, s1, v0
	v_cndmask_b32_e64 v0, 0, 1, s[6:7]
	v_lshl_add_u64 v[12:13], s[34:35], 0, v[10:11]
	v_mov_b32_e32 v9, v11
	s_lshl_b32 s3, s2, 7
	s_lshl_b32 s14, s82, 7
	s_mul_i32 s15, s82, 0xc0000
	s_movk_i32 s16, 0x1000
	v_cmp_ne_u32_e64 s[0:1], 1, v0
	s_mov_b32 s17, s2
	s_branch .LBB0_1395

.LBB0_1429:
	s_or_b64 exec, exec, s[12:13]
	s_bitcmp1_b32 s2, 3
	s_cbranch_scc1 .Lp18_conv
.Lp18_end:
.LBB0_1430:
	s_cmp_gt_i32 s85, 19
	s_cselect_b64 s[0:1], -1, 0
	s_and_b64 s[4:5], s[10:11], s[0:1]
	s_andn2_b64 vcc, exec, s[4:5]
	s_cbranch_vccnz .LBB0_1484
	s_waitcnt vmcnt(0)
	s_waitcnt lgkmcnt(0)
	s_barrier
	s_and_saveexec_b64 s[4:5], s[94:95]
	s_cbranch_execz .LBB0_1483
	s_add_i32 s3, 0, 0x24800
	v_mov_b32_e32 v0, s3
	s_waitcnt vmcnt(0) expcnt(0) lgkmcnt(0)
	ds_read_b32 v2, v0
	s_add_i32 s3, 0, 0x24804
	v_mov_b32_e32 v0, s3
	ds_read_b32 v0, v0
	s_waitcnt lgkmcnt(1)
	v_cmp_ne_u32_e32 vcc, 0, v2
	s_cbranch_vccnz .LBB0_1447
	s_add_u32 s6, s34, 0x3e00200
	s_addc_u32 s7, s35, 0
	s_add_u32 s8, s34, 0x3e00400
	s_addc_u32 s9, s35, 0
	s_add_u32 s10, s34, 0x3e00500
	s_addc_u32 s11, s35, 0
	s_add_u32 s12, s34, 0x3e00600
	s_addc_u32 s13, s35, 0
	s_add_u32 s14, s34, 0x3e00700
	s_addc_u32 s15, s35, 0
	s_add_u32 s16, s34, 0x3e00800
	s_addc_u32 s17, s35, 0
	s_add_u32 s18, s34, 0x3e00900
	s_addc_u32 s19, s35, 0
	s_add_u32 s22, s34, 0x3e00a00
	s_addc_u32 s23, s35, 0
	s_add_u32 s30, s34, 0x3e00b00
	s_addc_u32 s31, s35, 0
	s_add_u32 s36, s34, 0x3e00c00
	s_addc_u32 s37, s35, 0
	s_add_u32 s38, s34, 0x3e00d00
	s_addc_u32 s39, s35, 0
	s_add_u32 s40, s34, 0x3e00e00
	s_addc_u32 s41, s35, 0
	s_add_u32 s42, s34, 0x3e00f00
	s_addc_u32 s43, s35, 0
	s_add_u32 s44, s34, 0x3e01000
	s_addc_u32 s45, s35, 0
	s_add_u32 s46, s34, 0x3e01100
	s_addc_u32 s47, s35, 0
	s_add_u32 s48, s34, 0x3e01200
	s_addc_u32 s49, s35, 0
	s_mul_i32 s3, s83, s92
	s_add_u32 s50, s34, 0x3e01300
	s_mul_i32 s3, s3, s82
	s_addc_u32 s51, s35, 0
	s_mov_b32 s60, 1
	v_mov_b32_e32 v16, 0
	s_branch .LBB0_1435
